# attention loop row sums: v_pk_add_f32 replaced by scalar v_add_f32 pairs (packed f32 beside MFMAs costs more)
# speedup vs baseline: 1.0500x; 1.0092x over previous
; DI void attn_tile8(const Params& p, int bh, int qt, char* smem) {
;     ...
;     {
;       bf16x8 kf[2][4];
; #pragma unroll
;       for (int kb = 0; kb < 4; ++kb) kf[0][kb] = *(const bf16x8*)(Ks + (kb * 32 + lr) * 208 + lh * 16);
; #pragma unroll
;       for (int s = 0; s < 6; ++s) {
;         if (s < 5) {
; #pragma unroll
;           for (int kb = 0; kb < 4; ++kb) kf[(s + 1) & 1][kb] = *(const bf16x8*)(Ks + (kb * 32 + lr) * 208 + (s + 1) * 32 + lh * 16);
;         }
;         __builtin_amdgcn_sched_barrier(0);
;         __builtin_amdgcn_s_setprio(1);
; #pragma unroll
;         for (int kb = 0; kb < 4; ++kb) st[kb] = MFMA32(kf[s & 1][kb], qf[s], st[kb]);
;         __builtin_amdgcn_s_setprio(0);
;         __builtin_amdgcn_sched_barrier(0);
;       }
;     }
;     float mx = st[0][0];
; #pragma unroll
;     for (int kb = 0; kb < 4; ++kb)
; #pragma unroll
;       for (int i = 0; i < 16; ++i) mx = fmaxf(mx, st[kb][i]);
;     mx = fmaxf(mx, __shfl_xor(mx, 32));
;     const float mn = fmaxf(m, mx);
;     const float alpha = __builtin_amdgcn_exp2f(m - mn);
;     m = mn;
;     float ps = 0.f;
; #pragma unroll
;     for (int kb = 0; kb < 4; ++kb)
; #pragma unroll
;       for (int i = 0; i < 16; ++i) { st[kb][i] = __builtin_amdgcn_exp2f(st[kb][i] - mn); ps += st[kb][i]; }
;     lsum = lsum * alpha + ps;
; #pragma unroll
;     for (int i = 0; i < 16; ++i) { O[0][i] *= alpha; O[1][i] *= alpha; }
;     {
;       u32x4 vfr[2][2];
; #pragma unroll
;       for (int vb = 0; vb < 2; ++vb) {
;         const char* vp = Vs + (vb * 32 + lr) * VROW + (4 * lh) * 2;
;         const uint2 v0 = *(const uint2*)(vp);
;         const uint2 v1 = *(const uint2*)(vp + 16);
;         vfr[0][vb] = (u32x4){v0.x, v0.y, v1.x, v1.y};
;       }
; #pragma unroll
;       for (int step = 0; step < 8; ++step) {
;         const int kb = step >> 1, s2 = step & 1;
;         if (step < 7) {
;           const int kb2 = (step + 1) >> 1, s22 = (step + 1) & 1;
; #pragma unroll
;           for (int vb = 0; vb < 2; ++vb) {
;             const char* vp = Vs + (vb * 32 + lr) * VROW + (kb2 * 32 + 16 * s22 + 4 * lh) * 2;
;             const uint2 v0 = *(const uint2*)(vp);
;             const uint2 v1 = *(const uint2*)(vp + 16);
;             vfr[(step + 1) & 1][vb] = (u32x4){v0.x, v0.y, v1.x, v1.y};
;           }
;         }
;         u32x4 pk;
;         pk.x = pack2(st[kb][8 * s2 + 0], st[kb][8 * s2 + 1]);
.Lattn_noresc:
	ds_read_b128 v[180:183], v177 offset:0
	ds_read_b128 v[184:187], v177 offset:32
	ds_read_b128 v[188:191], v177 offset:64
	ds_read_b128 v[200:203], v177 offset:96
	v_mfma_f32_32x32x16_bf16 v[80:95], v[214:217], v[218:221], 0
	s_waitcnt lgkmcnt(3)
	v_mfma_f32_32x32x16_bf16 v[80:95], v[180:183], v[96:99], v[80:95]
	ds_read_b128 v[180:183], v177 offset:128
	s_waitcnt lgkmcnt(3)
	v_mfma_f32_32x32x16_bf16 v[80:95], v[184:187], v[100:103], v[80:95]
	ds_read_b128 v[184:187], v177 offset:160
	s_waitcnt lgkmcnt(3)
	v_mfma_f32_32x32x16_bf16 v[80:95], v[188:191], v[104:107], v[80:95]
	ds_read_b128 v[188:191], v177 offset:6656
	s_waitcnt lgkmcnt(3)
	v_mfma_f32_32x32x16_bf16 v[80:95], v[200:203], v[108:111], v[80:95]
	ds_read_b128 v[200:203], v177 offset:6688
	s_waitcnt lgkmcnt(3)
	v_mfma_f32_32x32x16_bf16 v[80:95], v[180:183], v[112:115], v[80:95]
	ds_read_b128 v[180:183], v177 offset:6720
	s_waitcnt lgkmcnt(3)
	v_mfma_f32_32x32x16_bf16 v[80:95], v[184:187], v[116:119], v[80:95]
	ds_read_b128 v[184:187], v177 offset:6752
	v_mfma_f32_32x32x16_bf16 v[64:79], v[214:217], v[218:221], 0
	s_waitcnt lgkmcnt(3)
	v_mfma_f32_32x32x16_bf16 v[64:79], v[188:191], v[96:99], v[64:79]
	ds_read_b128 v[188:191], v177 offset:6784
	s_waitcnt lgkmcnt(3)
	v_mfma_f32_32x32x16_bf16 v[64:79], v[200:203], v[100:103], v[64:79]
	ds_read_b128 v[200:203], v177 offset:6816
	s_waitcnt lgkmcnt(3)
	v_mfma_f32_32x32x16_bf16 v[64:79], v[180:183], v[104:107], v[64:79]
	ds_read_b128 v[180:183], v177 offset:13312
	s_nop 0
	v_max_f32_e32 v232, v80, v81
	v_max3_f32 v232, v232, v82, v83
	v_max3_f32 v232, v232, v84, v85
	v_max3_f32 v232, v232, v86, v87
	v_max3_f32 v232, v232, v88, v89
	v_max3_f32 v232, v232, v90, v91
	v_max3_f32 v232, v232, v92, v93
	v_max3_f32 v232, v232, v94, v95
	ds_bpermute_b32 v233, v175, v232
	v_exp_f32_e32 v80, v80
	v_exp_f32_e32 v81, v81
	v_exp_f32_e32 v82, v82
	v_exp_f32_e32 v83, v83
	s_waitcnt lgkmcnt(4)
	v_mfma_f32_32x32x16_bf16 v[64:79], v[184:187], v[108:111], v[64:79]
	ds_read_b128 v[184:187], v177 offset:13344
	v_exp_f32_e32 v84, v84
	v_exp_f32_e32 v85, v85
	v_exp_f32_e32 v86, v86
	v_exp_f32_e32 v87, v87
	v_exp_f32_e32 v88, v88
	v_exp_f32_e32 v89, v89
	v_exp_f32_e32 v90, v90
	v_exp_f32_e32 v91, v91
	v_exp_f32_e32 v92, v92
	v_exp_f32_e32 v93, v93
	v_exp_f32_e32 v94, v94
	v_exp_f32_e32 v95, v95
	s_waitcnt lgkmcnt(4)
	v_mfma_f32_32x32x16_bf16 v[64:79], v[188:191], v[112:115], v[64:79]
	ds_read_b128 v[188:191], v177 offset:13376
	v_add_f32_e32 v238, v238, v80
	v_add_f32_e32 v239, v239, v81
	v_add_f32_e32 v238, v238, v82
	v_add_f32_e32 v239, v239, v83
	v_add_f32_e32 v238, v238, v84
	v_add_f32_e32 v239, v239, v85
	v_add_f32_e32 v238, v238, v86
	v_add_f32_e32 v239, v239, v87
	v_add_f32_e32 v238, v238, v88
	v_add_f32_e32 v239, v239, v89
	v_add_f32_e32 v238, v238, v90
	v_add_f32_e32 v239, v239, v91
	s_waitcnt lgkmcnt(4)
	v_mfma_f32_32x32x16_bf16 v[64:79], v[200:203], v[116:119], v[64:79]
	ds_read_b128 v[200:203], v177 offset:13408
	v_add_f32_e32 v238, v238, v92
	v_add_f32_e32 v239, v239, v93
	v_add_f32_e32 v238, v238, v94
	v_add_f32_e32 v239, v239, v95
	v_cvt_pk_bf16_f32 v222, v80, v81
	v_cvt_pk_bf16_f32 v223, v82, v83
	v_cvt_pk_bf16_f32 v224, v84, v85
	v_cvt_pk_bf16_f32 v225, v86, v87
	v_cvt_pk_bf16_f32 v226, v88, v89
	v_cvt_pk_bf16_f32 v227, v90, v91
	v_cvt_pk_bf16_f32 v228, v92, v93
	v_cvt_pk_bf16_f32 v229, v94, v95
	ds_read2_b64 v[80:83], v199 offset0:0 offset1:2
	ds_read2_b64 v[84:87], v179 offset0:32 offset1:34
	ds_read2_b64 v[88:91], v199 offset0:4 offset1:6
	ds_read2_b64 v[92:95], v179 offset0:36 offset1:38
	v_mfma_f32_32x32x16_bf16 v[48:63], v[214:217], v[218:221], 0
	s_waitcnt lgkmcnt(8)
	v_mfma_f32_32x32x16_bf16 v[48:63], v[180:183], v[96:99], v[48:63]
	ds_read_b128 v[180:183], v177 offset:13440
	s_waitcnt lgkmcnt(7)
	v_mfma_f32_32x32x16_bf16 v[48:63], v[184:187], v[100:103], v[48:63]
	ds_read_b128 v[184:187], v177 offset:13472
	s_waitcnt lgkmcnt(5)
	v_mfma_f32_32x32x16_bf16 v[16:31], v[80:83], v[222:225], v[16:31]
	v_exp_f32_e32 v64, v64
	v_exp_f32_e32 v65, v65
	v_exp_f32_e32 v66, v66
	v_exp_f32_e32 v67, v67
	v_exp_f32_e32 v68, v68
	s_waitcnt lgkmcnt(4)
	v_mfma_f32_32x32x16_bf16 v[0:15], v[84:87], v[222:225], v[0:15]
	v_exp_f32_e32 v69, v69
	v_exp_f32_e32 v70, v70
	v_exp_f32_e32 v71, v71
	v_exp_f32_e32 v72, v72
	v_exp_f32_e32 v73, v73
	v_mfma_f32_32x32x16_bf16 v[48:63], v[188:191], v[104:107], v[48:63]
	ds_read_b128 v[188:191], v177 offset:19968
	v_exp_f32_e32 v74, v74
	v_exp_f32_e32 v75, v75
	v_exp_f32_e32 v76, v76
	v_exp_f32_e32 v77, v77
	v_exp_f32_e32 v78, v78
	v_mfma_f32_32x32x16_bf16 v[48:63], v[200:203], v[108:111], v[48:63]
	ds_read_b128 v[200:203], v177 offset:20000
	v_exp_f32_e32 v79, v79
	v_add_f32_e32 v238, v238, v64
	v_add_f32_e32 v239, v239, v65
	v_add_f32_e32 v238, v238, v66
	v_add_f32_e32 v239, v239, v67
	s_waitcnt lgkmcnt(5)
	v_mfma_f32_32x32x16_bf16 v[16:31], v[88:91], v[226:229], v[16:31]
	v_add_f32_e32 v238, v238, v68
	v_add_f32_e32 v239, v239, v69
	v_add_f32_e32 v238, v238, v70
	v_add_f32_e32 v239, v239, v71
	v_add_f32_e32 v238, v238, v72
	s_waitcnt lgkmcnt(4)
	v_mfma_f32_32x32x16_bf16 v[0:15], v[92:95], v[226:229], v[0:15]
	v_add_f32_e32 v239, v239, v73
	v_add_f32_e32 v238, v238, v74
	v_add_f32_e32 v239, v239, v75
	v_add_f32_e32 v238, v238, v76
	v_add_f32_e32 v239, v239, v77
	s_waitcnt lgkmcnt(3)
	v_mfma_f32_32x32x16_bf16 v[48:63], v[180:183], v[112:115], v[48:63]
	ds_read_b128 v[180:183], v177 offset:20032
	v_add_f32_e32 v238, v238, v78
	v_add_f32_e32 v239, v239, v79
	v_cvt_pk_bf16_f32 v222, v64, v65
	v_cvt_pk_bf16_f32 v223, v66, v67
	v_cvt_pk_bf16_f32 v224, v68, v69
	s_waitcnt lgkmcnt(3)
; DI void attn_tile8(const Params& p, int bh, int qt, char* smem) {
;     ...
;   auto store_tiles = [&](int st) {
;     char* Ks = smem + st * STAGE;
;     char* Vs = Ks + VOFF;
; #pragma unroll
;     for (int i = 0; i < 3; ++i) {
;       const int idx = tid + 512 * i, key = idx / 12, ch = idx % 12;
;       *(u32x4*)(Ks + key * 208 + ch * 16) = rk[i];
;     }
; #pragma unroll
;     for (int i = 0; i < 2; ++i) {
;       const int idx = tid + 512 * i, vd = idx >> 4, ch = idx & 15;
;     ...
;     for (int kb = 0; kb < 4; ++kb)
; #pragma unroll
;       for (int i = 0; i < 16; ++i) { st[kb][i] = __builtin_amdgcn_exp2f(st[kb][i] - mn); ps += st[kb][i]; }
;     lsum = lsum * alpha + ps;
; #pragma unroll
;     for (int i = 0; i < 16; ++i) { O[0][i] *= alpha; O[1][i] *= alpha; }
;     {
;       u32x4 vfr[2][2];
; #pragma unroll
;       for (int vb = 0; vb < 2; ++vb) {
;         const char* vp = Vs + (vb * 32 + lr) * VROW + (4 * lh) * 2;
;         const uint2 v0 = *(const uint2*)(vp);
;         const uint2 v1 = *(const uint2*)(vp + 16);
;         vfr[0][vb] = (u32x4){v0.x, v0.y, v1.x, v1.y};
;       }
; #pragma unroll
;       for (int step = 0; step < 8; ++step) {
;         const int kb = step >> 1, s2 = step & 1;
;         if (step < 7) {
;           const int kb2 = (step + 1) >> 1, s22 = (step + 1) & 1;
; #pragma unroll
;           for (int vb = 0; vb < 2; ++vb) {
;             const char* vp = Vs + (vb * 32 + lr) * VROW + (kb2 * 32 + 16 * s22 + 4 * lh) * 2;
;             const uint2 v0 = *(const uint2*)(vp);
;             const uint2 v1 = *(const uint2*)(vp + 16);
;             vfr[(step + 1) & 1][vb] = (u32x4){v0.x, v0.y, v1.x, v1.y};
;           }
;         }
;         u32x4 pk;
;         pk.x = pack2(st[kb][8 * s2 + 0], st[kb][8 * s2 + 1]);
;         pk.y = pack2(st[kb][8 * s2 + 2], st[kb][8 * s2 + 3]);
;         pk.z = pack2(st[kb][8 * s2 + 4], st[kb][8 * s2 + 5]);
;         pk.w = pack2(st[kb][8 * s2 + 6], st[kb][8 * s2 + 7]);
;         const bf16x8 bfrag = __builtin_bit_cast(bf16x8, pk);
;         __builtin_amdgcn_sched_barrier(0);
;         O[0] = MFMA32(__builtin_bit_cast(bf16x8, vfr[step & 1][0]), bfrag, O[0]);
;         O[1] = MFMA32(__builtin_bit_cast(bf16x8, vfr[step & 1][1]), bfrag, O[1]);
;         __builtin_amdgcn_sched_barrier(0);
;       }
;     }
;     if (more) store_tiles((kt + 1) & 1);
;     __syncthreads();
;   }
	v_mfma_f32_32x32x16_bf16 v[48:63], v[184:187], v[116:119], v[48:63]
	ds_read_b128 v[184:187], v177 offset:20064
	v_cvt_pk_bf16_f32 v225, v70, v71
	v_cvt_pk_bf16_f32 v226, v72, v73
	v_cvt_pk_bf16_f32 v227, v74, v75
	v_cvt_pk_bf16_f32 v228, v76, v77
	v_cvt_pk_bf16_f32 v229, v78, v79
	ds_read2_b64 v[64:67], v199 offset0:8 offset1:10
	ds_read2_b64 v[68:71], v179 offset0:40 offset1:42
	ds_read2_b64 v[72:75], v199 offset0:12 offset1:14
	ds_read2_b64 v[76:79], v179 offset0:44 offset1:46
	v_mfma_f32_32x32x16_bf16 v[32:47], v[214:217], v[218:221], 0
	s_waitcnt lgkmcnt(7)
	v_mfma_f32_32x32x16_bf16 v[32:47], v[188:191], v[96:99], v[32:47]
	ds_read_b128 v[188:191], v177 offset:20096
	s_waitcnt lgkmcnt(7)
	v_mfma_f32_32x32x16_bf16 v[32:47], v[200:203], v[100:103], v[32:47]
	ds_read_b128 v[200:203], v177 offset:20128
	s_waitcnt lgkmcnt(5)
	v_mfma_f32_32x32x16_bf16 v[16:31], v[64:67], v[222:225], v[16:31]
	v_exp_f32_e32 v48, v48
	v_exp_f32_e32 v49, v49
	v_exp_f32_e32 v50, v50
	v_exp_f32_e32 v51, v51
	v_exp_f32_e32 v52, v52
	s_waitcnt lgkmcnt(4)
	v_mfma_f32_32x32x16_bf16 v[0:15], v[68:71], v[222:225], v[0:15]
	v_exp_f32_e32 v53, v53
	v_exp_f32_e32 v54, v54
	v_exp_f32_e32 v55, v55
	v_exp_f32_e32 v56, v56
	v_exp_f32_e32 v57, v57
	v_mfma_f32_32x32x16_bf16 v[32:47], v[180:183], v[104:107], v[32:47]
	v_exp_f32_e32 v58, v58
	v_exp_f32_e32 v59, v59
	v_exp_f32_e32 v60, v60
	v_exp_f32_e32 v61, v61
	v_exp_f32_e32 v62, v62
	v_mfma_f32_32x32x16_bf16 v[32:47], v[184:187], v[108:111], v[32:47]
	v_exp_f32_e32 v63, v63
	v_add_f32_e32 v238, v238, v48
	v_add_f32_e32 v239, v239, v49
	v_add_f32_e32 v238, v238, v50
	v_add_f32_e32 v239, v239, v51
	s_waitcnt lgkmcnt(3)
	v_mfma_f32_32x32x16_bf16 v[16:31], v[72:75], v[226:229], v[16:31]
	v_add_f32_e32 v238, v238, v52
	v_add_f32_e32 v239, v239, v53
	v_add_f32_e32 v238, v238, v54
	v_add_f32_e32 v239, v239, v55
	v_add_f32_e32 v238, v238, v56
	s_waitcnt lgkmcnt(2)
	v_mfma_f32_32x32x16_bf16 v[0:15], v[76:79], v[226:229], v[0:15]
	v_add_f32_e32 v239, v239, v57
	v_add_f32_e32 v238, v238, v58
	v_add_f32_e32 v239, v239, v59
	v_add_f32_e32 v238, v238, v60
	v_add_f32_e32 v239, v239, v61
	s_waitcnt lgkmcnt(1)
	v_mfma_f32_32x32x16_bf16 v[32:47], v[188:191], v[112:115], v[32:47]
	v_add_f32_e32 v238, v238, v62
	v_add_f32_e32 v239, v239, v63
	v_cvt_pk_bf16_f32 v222, v48, v49
	v_cvt_pk_bf16_f32 v223, v50, v51
	v_cvt_pk_bf16_f32 v224, v52, v53
	s_waitcnt lgkmcnt(0)
	v_mfma_f32_32x32x16_bf16 v[32:47], v[200:203], v[116:119], v[32:47]
	v_cvt_pk_bf16_f32 v225, v54, v55
	v_cvt_pk_bf16_f32 v226, v56, v57
	v_cvt_pk_bf16_f32 v227, v58, v59
	v_cvt_pk_bf16_f32 v228, v60, v61
	v_cvt_pk_bf16_f32 v229, v62, v63
	ds_read2_b64 v[48:51], v199 offset0:16 offset1:18
	ds_read2_b64 v[52:55], v179 offset0:48 offset1:50
	ds_read2_b64 v[56:59], v199 offset0:20 offset1:22
	ds_read2_b64 v[60:63], v179 offset0:52 offset1:54
	s_waitcnt lgkmcnt(3)
	v_mfma_f32_32x32x16_bf16 v[16:31], v[48:51], v[222:225], v[16:31]
	s_nop 0
	v_exp_f32_e32 v32, v32
	v_exp_f32_e32 v33, v33
	v_exp_f32_e32 v34, v34
	v_exp_f32_e32 v35, v35
	v_exp_f32_e32 v36, v36
	v_exp_f32_e32 v37, v37
	v_exp_f32_e32 v38, v38
	v_exp_f32_e32 v39, v39
	v_exp_f32_e32 v40, v40
	v_exp_f32_e32 v41, v41
	s_waitcnt lgkmcnt(2)
	v_mfma_f32_32x32x16_bf16 v[0:15], v[52:55], v[222:225], v[0:15]
	v_exp_f32_e32 v42, v42
	v_exp_f32_e32 v43, v43
	v_exp_f32_e32 v44, v44
	v_exp_f32_e32 v45, v45
	v_exp_f32_e32 v46, v46
	v_exp_f32_e32 v47, v47
	v_add_f32_e32 v238, v238, v32
	v_add_f32_e32 v239, v239, v33
	v_add_f32_e32 v238, v238, v34
	v_add_f32_e32 v239, v239, v35
	s_waitcnt lgkmcnt(1)
	v_mfma_f32_32x32x16_bf16 v[16:31], v[56:59], v[226:229], v[16:31]
	v_add_f32_e32 v238, v238, v36
	v_add_f32_e32 v239, v239, v37
	v_add_f32_e32 v238, v238, v38
	v_add_f32_e32 v239, v239, v39
	v_add_f32_e32 v238, v238, v40
	v_add_f32_e32 v239, v239, v41
	v_add_f32_e32 v238, v238, v42
	v_add_f32_e32 v239, v239, v43
	v_add_f32_e32 v238, v238, v44
	v_add_f32_e32 v239, v239, v45
	s_waitcnt lgkmcnt(0)
	v_mfma_f32_32x32x16_bf16 v[0:15], v[60:63], v[226:229], v[0:15]
	v_add_f32_e32 v238, v238, v46
	v_add_f32_e32 v239, v239, v47
	v_cvt_pk_bf16_f32 v222, v32, v33
	v_cvt_pk_bf16_f32 v223, v34, v35
	v_cvt_pk_bf16_f32 v224, v36, v37
	v_cvt_pk_bf16_f32 v225, v38, v39
	v_cvt_pk_bf16_f32 v226, v40, v41
	v_cvt_pk_bf16_f32 v227, v42, v43
	v_cvt_pk_bf16_f32 v228, v44, v45
	v_cvt_pk_bf16_f32 v229, v46, v47
	ds_read2_b64 v[32:35], v199 offset0:24 offset1:26
	ds_read2_b64 v[36:39], v179 offset0:56 offset1:58
	ds_read2_b64 v[40:43], v199 offset0:28 offset1:30
	ds_read2_b64 v[44:47], v179 offset0:60 offset1:62
	s_bitcmp1_b32 s23, 0
	s_cselect_b32 s20, 0xaa00, 0
	v_add3_u32 v213, s20, v147, v144
	s_waitcnt vmcnt(4)
	ds_write_b128 v213, v[120:123]
	v_add3_u32 v213, s20, v149, v146
	s_waitcnt vmcnt(3)
	ds_write_b128 v213, v[124:127]
	v_add3_u32 v213, s20, v151, v148
	s_waitcnt vmcnt(2)
	ds_write_b128 v213, v[128:131]
	v_add_u32_e32 v213, s20, v173
	s_movk_i32 s21, 0x6800
	v_add3_u32 v213, v213, v150, s21
	s_waitcnt vmcnt(1)
	ds_write2_b64 v213, v[132:133], v[134:135] offset1:1
	v_add_u32_e32 v213, s20, v174
	v_add3_u32 v213, v213, v150, s21
	s_waitcnt vmcnt(0)
	ds_write2_b64 v213, v[136:137], v[138:139] offset1:1
	s_waitcnt lgkmcnt(8)
	v_mfma_f32_32x32x16_bf16 v[16:31], v[32:35], v[222:225], v[16:31]
	s_waitcnt lgkmcnt(7)
	v_mfma_f32_32x32x16_bf16 v[0:15], v[36:39], v[222:225], v[0:15]
	s_waitcnt lgkmcnt(6)
	v_mfma_f32_32x32x16_bf16 v[16:31], v[40:43], v[226:229], v[16:31]
	s_waitcnt lgkmcnt(5)
	v_mfma_f32_32x32x16_bf16 v[0:15], v[44:47], v[226:229], v[0:15]
	s_mov_b64 s[20:21], 0x100
	s_add_u32 s18, s18, 0x20000
	v_lshl_add_u64 v[160:161], v[160:161], 0, s[20:21]
	v_lshl_add_u64 v[162:163], v[162:163], 0, s[20:21]
	s_addc_u32 s19, s19, 0
	s_mov_b64 s[20:21], 0x2000
	s_cmp_lg_u32 s18, 0x440000
	v_lshl_add_u64 v[152:153], v[152:153], 0, s[20:21]
	s_waitcnt lgkmcnt(0)
	s_barrier
	s_cbranch_scc0 .Lattn_exit
	s_mov_b32 s31, s23
	s_branch .Lattn_loop
